# dequeue: wave 0 waits for the prefetched ticket with a counted vmcnt (4 epilogue stores younger) or no wait (A: covered by gain-load wait) instead of draining its output stores
# baseline (speedup 1.0000x reference)
; DI void attn_phase(const Params& P, char* shm) {
;     ...
;             if (tid == 0) su[0] = atomicAdd(cnt, 1u);
.LBB0_320:
	s_and_saveexec_b64 s[0:1], s[34:35]
	s_cbranch_execz .LBB0_324
	v_readlane_b32 s2, v255, 61
	s_cmp_eq_u32 s2, 0
	s_cbranch_scc1 .Ldq_nopf
	s_cmp_eq_u32 s2, 3
	s_cbranch_scc1 .Ldq_w4
	s_cmp_eq_u32 s2, 2
	s_cbranch_scc1 .Ldq_w
	s_waitcnt vmcnt(0)
	s_branch .Ldq_w

; DI void attn_phase(const Params& P, char* shm) {
;     ...
;             if (tid == 0) su[0] = atomicAdd(cnt, 1u);
.Ldq_w:
	v_mov_b32_e32 v1, s87
	ds_write_b32 v1, v218
	s_branch .LBB0_324

; template <int KIND> DI void attn_unit(const Params& P, int b, int h, int qb, char* shm, float lam, bool dry = false) {
;     ...
;     const float rl = __builtin_amdgcn_rcpf(swapsum(lsum));
;     bf16_t* orow = P.Qp + (rowbase + qrow0 + r32) * PITCH + ((KIND == 0) ? h * 128 : qoff);
;     ATT_WAIT_BAR();
;     if (KIND == 0) {
;         LAS float* comb = (LAS float*)shm3 + (size_t)(wid & 3) * 4096 + lane;
;         if (m == 1) {
; #pragma unroll
;             for (int db = 0; db < NDB; ++db)
; #pragma unroll
;                 for (int r = 0; r < 16; ++r) comb[(db * 16 + r) * 64] = o[db][r] * rl;
;         }
;         ATT_WAIT_BAR();
;         if (m == 0) {
;             float ss = 0.f;
; #pragma unroll
;             for (int db = 0; db < NDB; ++db)
; #pragma unroll
;                 for (int r = 0; r < 16; ++r) { const float d = o[db][r] * rl - lam * comb[(db * 16 + r) * 64]; o[db][r] = d; ss += d * d; }
;             ss = swapsum(ss);
;             const float sc = __builtin_amdgcn_rsqf(ss * (1.0f / 128.0f) + RMS_EPS) * (1.0f - P.lam_init);
; #pragma unroll
;             for (int db = 0; db < NDB; ++db)
; #pragma unroll
;                 for (int g = 0; g < 4; g += 2) { u32x2 wp[2];
; #pragma unroll
;                     for (int e = 0; e < 2; ++e) { const f32x4 sg = *(const f32x4*)(P.subg + db * 32 + 8 * (g + e) + 4 * hi); const int r = 4 * (g + e);
;                         wp[e].x = cvtpk(o[db][r] * sc * sg[0], o[db][r + 1] * sc * sg[1]); wp[e].y = cvtpk(o[db][r + 2] * sc * sg[2], o[db][r + 3] * sc * sg[3]); }
;                     store_pair16(orow + db * 32 + 8 * g, hi, wp[0], wp[1], dry); }
;         }
;         ATT_WAIT_BAR();
;     } else {
; #pragma unroll
;         for (int db = 0; db < NDB; ++db)
; #pragma unroll
;             for (int g = 0; g < 4; g += 2) { u32x2 wp[2];
; #pragma unroll
;                 for (int e = 0; e < 2; ++e) { const int r = 4 * (g + e); wp[e].x = cvtpk(o[db][r] * rl, o[db][r + 1] * rl); wp[e].y = cvtpk(o[db][r + 2] * rl, o[db][r + 3] * rl); }
;                 store_pair16(orow + db * 32 + 8 * g, hi, wp[0], wp[1], dry); }
; DI void attn_phase(const Params& P, char* shm) {
;     ...
;         const unsigned q = (xcd + k) & 7u; unsigned* cnt = P.counter + 16 * q;
;         for (;;) {
;             if (tid == 0) su[0] = atomicAdd(cnt, 1u);
;             ATT_WAIT_BAR();
;             const unsigned ui = su[0];
;             ATT_WAIT_BAR();
.LBB0_364:
	v_mov_b32_e32 v0, v169
	s_nop 1
	v_permlane32_swap_b32_e32 v169, v0
	v_add_f32_e32 v0, v169, v0
	v_rcp_f32_e32 v0, v0
	s_waitcnt vmcnt(0) lgkmcnt(0)
	s_barrier
	v_readlane_b32 s100, v255, 47
	v_readlane_b32 s101, v255, 48
	v_readlane_b32 vcc_lo, v255, 39
	v_readlane_b32 vcc_hi, v255, 40
	v_mov_b32_e32 v218, 1
	v_mov_b32_e32 v219, 0
	s_mov_b64 exec, vcc
	s_nop 1
	global_atomic_add v218, v219, v218, s[100:101] sc0
	s_mov_b64 exec, -1
	v_writelane_b32 v255, 3, 61
	s_nop 0
	v_readlane_b32 s96, v255, 32
	v_readlane_b32 s64, v255, 30
	v_pk_mul_f32 v[4:5], v[52:53], v[0:1] op_sel_hi:[1,0]
	v_pk_mul_f32 v[6:7], v[54:55], v[0:1] op_sel_hi:[1,0]
	v_cvt_pk_bf16_f32 v4, v4, v5
	v_cvt_pk_bf16_f32 v5, v6, v7
	v_pk_mul_f32 v[6:7], v[56:57], v[0:1] op_sel_hi:[1,0]
	v_pk_mul_f32 v[8:9], v[58:59], v[0:1] op_sel_hi:[1,0]
	v_cvt_pk_bf16_f32 v6, v6, v7
	v_cvt_pk_bf16_f32 v7, v8, v9
	s_nop 0
	v_permlane32_swap_b32_e32 v4, v6
	v_permlane32_swap_b32_e32 v5, v7
	global_store_dwordx4 v[162:163], v[4:7], off offset:2048
	v_pk_mul_f32 v[8:9], v[66:67], v[0:1] op_sel_hi:[1,0]
	v_readlane_b32 s66, v254, 32
	v_pk_mul_f32 v[4:5], v[60:61], v[0:1] op_sel_hi:[1,0]
	v_pk_mul_f32 v[6:7], v[62:63], v[0:1] op_sel_hi:[1,0]
	v_cvt_pk_bf16_f32 v4, v4, v5
	v_cvt_pk_bf16_f32 v5, v6, v7
	v_pk_mul_f32 v[6:7], v[64:65], v[0:1] op_sel_hi:[1,0]
	v_readlane_b32 s68, v254, 34
	v_cvt_pk_bf16_f32 v6, v6, v7
	v_cvt_pk_bf16_f32 v7, v8, v9
	s_nop 0
	v_permlane32_swap_b32_e32 v4, v6
	v_permlane32_swap_b32_e32 v5, v7
	global_store_dwordx4 v[162:163], v[4:7], off offset:2080
	v_pk_mul_f32 v[8:9], v[42:43], v[0:1] op_sel_hi:[1,0]
	v_readlane_b32 s97, v255, 33
	v_pk_mul_f32 v[4:5], v[36:37], v[0:1] op_sel_hi:[1,0]
	v_pk_mul_f32 v[6:7], v[38:39], v[0:1] op_sel_hi:[1,0]
	v_cvt_pk_bf16_f32 v4, v4, v5
	v_cvt_pk_bf16_f32 v5, v6, v7
	v_pk_mul_f32 v[6:7], v[40:41], v[0:1] op_sel_hi:[1,0]
	v_readlane_b32 s58, v255, 9
	v_cvt_pk_bf16_f32 v6, v6, v7
	v_cvt_pk_bf16_f32 v7, v8, v9
	s_nop 0
	v_permlane32_swap_b32_e32 v4, v6
	v_permlane32_swap_b32_e32 v5, v7
	global_store_dwordx4 v[162:163], v[4:7], off offset:2112
	v_readlane_b32 s52, v255, 11
	v_readlane_b32 s36, v255, 13
	v_pk_mul_f32 v[4:5], v[44:45], v[0:1] op_sel_hi:[1,0]
	v_pk_mul_f32 v[6:7], v[46:47], v[0:1] op_sel_hi:[1,0]
	v_cvt_pk_bf16_f32 v4, v4, v5
	v_cvt_pk_bf16_f32 v5, v6, v7
	v_pk_mul_f32 v[6:7], v[48:49], v[0:1] op_sel_hi:[1,0]
	v_pk_mul_f32 v[0:1], v[50:51], v[0:1] op_sel_hi:[1,0]
	v_cvt_pk_bf16_f32 v6, v6, v7
	v_cvt_pk_bf16_f32 v7, v0, v1
	s_nop 0
	v_permlane32_swap_b32_e32 v4, v6
	v_permlane32_swap_b32_e32 v5, v7
	v_readlane_b32 s24, v255, 15
	v_readlane_b32 s22, v255, 35
	v_readlane_b32 s34, v255, 39
	v_readlane_b32 s42, v255, 47
	global_store_dwordx4 v[162:163], v[4:7], off offset:2144
	s_mov_b64 s[0:1], 0
	v_readlane_b32 s65, v255, 31
	v_readlane_b32 s67, v254, 33
	v_readlane_b32 s69, v254, 35
	v_readlane_b32 s70, v254, 36
	v_readlane_b32 s71, v254, 37
	v_readlane_b32 s72, v254, 38
	v_readlane_b32 s73, v254, 39
	v_readlane_b32 s74, v254, 40
	v_readlane_b32 s75, v254, 41
	v_readlane_b32 s76, v254, 42
	v_readlane_b32 s77, v254, 43
	v_readlane_b32 s78, v254, 44
	v_readlane_b32 s79, v254, 45
	v_readlane_b32 s80, v254, 46
	v_readlane_b32 s81, v254, 47
	v_readlane_b32 s82, v254, 48
	v_readlane_b32 s83, v254, 49
	s_mov_b32 s84, 0xffff0000
	s_mov_b32 s85, 0x43800000
	s_movk_i32 s86, 0xc00
	v_readlane_b32 s87, v254, 50
	s_mov_b32 s88, 0x40c00000
	s_movk_i32 s89, 0x83f
	s_movk_i32 s90, 0x7fff
	s_mov_b32 s91, 0x5400000
	s_mov_b64 s[92:93], 0x1000
	s_mov_b64 s[94:95], 0x200000
	s_mov_b64 s[50:51], 0x80
	s_mov_b64 s[30:31], 0x100
	s_mov_b32 s60, 0x3fb8aa3b
	s_mov_b64 s[62:63], 0x2000
	s_mov_b64 s[54:55], 0x202000
	s_mov_b64 s[56:57], 0x1e0800
	v_readlane_b32 s59, v255, 10
	v_readlane_b32 s53, v255, 12
	v_readlane_b32 s97, v254, 57
	v_readlane_b32 s37, v255, 14
	v_readlane_b32 s25, v255, 16
	v_readlane_b32 s61, v255, 34
	v_readlane_b32 s23, v255, 36
	v_readlane_b32 s26, v255, 37
	v_readlane_b32 s27, v255, 38
	v_readlane_b32 s35, v255, 40
	v_readlane_b32 s29, v255, 41
	v_readlane_b32 s38, v255, 42
	v_readlane_b32 s39, v255, 43
	v_readlane_b32 s40, v255, 44
	v_readlane_b32 s43, v255, 48
	v_readlane_b32 s41, v255, 46
	v_readlane_b32 s3, v255, 49
	v_readlane_b32 s15, v255, 51
	v_readlane_b32 s14, v255, 50
	v_readlane_b32 s16, v255, 52
	s_mul_i32 s10, s2, 24

; DI unsigned cvtpk(float lo, float hi) { f32x2_t v = {lo, hi}; bf16x2_t b = __builtin_convertvector(v, bf16x2_t); return __builtin_bit_cast(unsigned, b); }
; DI float swapsum(float m) { auto rr = __builtin_amdgcn_permlane32_swap(__float_as_uint(m), __float_as_uint(m), false, false); return __uint_as_float(rr[0]) + __uint_as_float(rr[1]); }
; #define ATT_WAIT_BAR() asm volatile("s_waitcnt vmcnt(0) lgkmcnt(0)\n\ts_barrier" ::: "memory")
; template <int KIND> DI void attn_unit(const Params& P, int b, int h, int qb, char* shm, float lam, bool dry = false) {
;     ...
;         ATT_WAIT_BAR();
;         if (m == 0) {
;             float ss = 0.f;
; #pragma unroll
;             for (int db = 0; db < NDB; ++db)
; #pragma unroll
;                 for (int r = 0; r < 16; ++r) { const float d = o[db][r] * rl - lam * comb[(db * 16 + r) * 64]; o[db][r] = d; ss += d * d; }
;             ss = swapsum(ss);
;             const float sc = __builtin_amdgcn_rsqf(ss * (1.0f / 128.0f) + RMS_EPS) * (1.0f - P.lam_init);
; #pragma unroll
;             for (int db = 0; db < NDB; ++db)
; #pragma unroll
;                 for (int g = 0; g < 4; g += 2) { u32x2 wp[2];
; #pragma unroll
;                     for (int e = 0; e < 2; ++e) { const f32x4 sg = *(const f32x4*)(P.subg + db * 32 + 8 * (g + e) + 4 * hi); const int r = 4 * (g + e);
;                         wp[e].x = cvtpk(o[db][r] * sc * sg[0], o[db][r + 1] * sc * sg[1]); wp[e].y = cvtpk(o[db][r + 2] * sc * sg[2], o[db][r + 3] * sc * sg[3]); }
.LBB0_414:
	s_waitcnt vmcnt(0) lgkmcnt(0)
	s_barrier
	s_cmpk_gt_u32 s12, 0xff
	s_cbranch_scc1 .LBB0_317
	ds_read2st64_b32 v[102:103], v4 offset1:1
	ds_read2st64_b32 v[98:99], v4 offset0:2 offset1:3
	ds_read2st64_b32 v[96:97], v4 offset0:4 offset1:5
	ds_read2st64_b32 v[92:93], v4 offset0:6 offset1:7
	ds_read2st64_b32 v[120:121], v4 offset0:8 offset1:9
	ds_read2st64_b32 v[122:123], v4 offset0:10 offset1:11
	ds_read2st64_b32 v[124:125], v4 offset0:12 offset1:13
	ds_read2st64_b32 v[126:127], v4 offset0:14 offset1:15
	ds_read2st64_b32 v[128:129], v4 offset0:16 offset1:17
	ds_read2st64_b32 v[130:131], v4 offset0:18 offset1:19
	ds_read2st64_b32 v[132:133], v4 offset0:20 offset1:21
	ds_read2st64_b32 v[134:135], v4 offset0:22 offset1:23
	ds_read2st64_b32 v[118:119], v4 offset0:24 offset1:25
	ds_read2st64_b32 v[136:137], v4 offset0:26 offset1:27
	ds_read2st64_b32 v[138:139], v4 offset0:28 offset1:29
	ds_read2st64_b32 v[140:141], v4 offset0:30 offset1:31
	ds_read2st64_b32 v[110:111], v4 offset0:32 offset1:33
	ds_read2st64_b32 v[112:113], v4 offset0:34 offset1:35
	ds_read2st64_b32 v[114:115], v4 offset0:36 offset1:37
	ds_read2st64_b32 v[116:117], v4 offset0:38 offset1:39
	ds_read2st64_b32 v[100:101], v4 offset0:40 offset1:41
	ds_read2st64_b32 v[104:105], v4 offset0:42 offset1:43
	ds_read2st64_b32 v[106:107], v4 offset0:44 offset1:45
	ds_read2st64_b32 v[108:109], v4 offset0:46 offset1:47
	ds_read2st64_b32 v[88:89], v4 offset0:48 offset1:49
	ds_read2st64_b32 v[90:91], v4 offset0:50 offset1:51
	ds_read2st64_b32 v[94:95], v4 offset0:52 offset1:53
	ds_read2st64_b32 v[18:19], v4 offset0:54 offset1:55
	ds_read2st64_b32 v[84:85], v4 offset0:56 offset1:57
	ds_read2st64_b32 v[86:87], v4 offset0:58 offset1:59
	ds_read2st64_b32 v[14:15], v4 offset0:60 offset1:61
	ds_read2st64_b32 v[4:5], v4 offset0:62 offset1:63
	s_lshl_b32 s20, s2, 1
	v_readlane_b32 s0, v255, 23
	v_lshl_add_u64 v[0:1], v[0:1], 0, s[20:21]
	v_lshlrev_b32_e32 v3, 2, v3
	s_waitcnt lgkmcnt(0)
	v_pk_mul_f32 v[4:5], v[188:189], v[4:5]
	v_readlane_b32 s1, v255, 24
	v_pk_fma_f32 v[12:13], v[34:35], v[16:17], v[4:5] op_sel_hi:[1,0,1] neg_lo:[0,0,1] neg_hi:[0,0,1]
	v_pk_mul_f32 v[34:35], v[188:189], v[92:93]
	v_lshlrev_b32_e32 v4, 1, v198
	v_pk_fma_f32 v[92:93], v[74:75], v[16:17], v[34:35] op_sel_hi:[1,0,1] neg_lo:[0,0,1] neg_hi:[0,0,1]
	v_pk_mul_f32 v[34:35], v[188:189], v[96:97]
	v_mov_b32_e32 v5, v2
	v_pk_fma_f32 v[96:97], v[72:73], v[16:17], v[34:35] op_sel_hi:[1,0,1] neg_lo:[0,0,1] neg_hi:[0,0,1]
	v_pk_mul_f32 v[34:35], v[188:189], v[98:99]
	v_lshl_add_u64 v[0:1], v[0:1], 0, v[4:5]
	v_pk_fma_f32 v[98:99], v[70:71], v[16:17], v[34:35] op_sel_hi:[1,0,1] neg_lo:[0,0,1] neg_hi:[0,0,1]
	v_pk_mul_f32 v[34:35], v[188:189], v[102:103]
	global_load_dwordx4 v[148:151], v3, s[0:1]
	global_load_dwordx4 v[152:155], v3, s[0:1] offset:32
	global_load_dwordx4 v[156:159], v3, s[0:1] offset:64
	global_load_dwordx4 v[160:163], v3, s[0:1] offset:96
	global_load_dwordx4 v[164:167], v3, s[0:1] offset:128
	global_load_dwordx4 v[168:171], v3, s[0:1] offset:160
	global_load_dwordx4 v[172:175], v3, s[0:1] offset:192
	global_load_dwordx4 v[176:179], v3, s[0:1] offset:224
	global_load_dwordx4 v[180:183], v3, s[0:1] offset:256
	global_load_dwordx4 v[184:187], v3, s[0:1] offset:288
	global_load_dwordx4 v[208:211], v3, s[0:1] offset:320
	global_load_dwordx4 v[220:223], v3, s[0:1] offset:352
	global_load_dwordx4 v[224:227], v3, s[0:1] offset:384
	global_load_dwordx4 v[228:231], v3, s[0:1] offset:416
	global_load_dwordx4 v[232:235], v3, s[0:1] offset:448
	global_load_dwordx4 v[190:193], v3, s[0:1] offset:480
	v_pk_fma_f32 v[102:103], v[68:69], v[16:17], v[34:35] op_sel_hi:[1,0,1] neg_lo:[0,0,1] neg_hi:[0,0,1]
	v_mul_f32_e32 v68, v99, v99
	v_mul_f32_e32 v34, v103, v103
	v_pk_fma_f32 v[34:35], v[102:103], v[102:103], v[34:35] op_sel_hi:[1,1,0]
	v_pk_mul_f32 v[18:19], v[188:189], v[18:19]
	v_pk_fma_f32 v[34:35], v[98:99], v[98:99], v[34:35]
	v_pk_fma_f32 v[18:19], v[26:27], v[16:17], v[18:19] op_sel_hi:[1,0,1] neg_lo:[0,0,1] neg_hi:[0,0,1]
	v_pk_add_f32 v[34:35], v[34:35], v[68:69] op_sel_hi:[1,0]
	v_mul_f32_e32 v68, v97, v97
	v_pk_fma_f32 v[34:35], v[96:97], v[96:97], v[34:35]
	v_pk_mul_f32 v[26:27], v[188:189], v[94:95]
	v_pk_add_f32 v[34:35], v[34:35], v[68:69] op_sel_hi:[1,0]
	v_mul_f32_e32 v68, v93, v93
	v_pk_fma_f32 v[34:35], v[92:93], v[92:93], v[34:35]
	v_pk_fma_f32 v[24:25], v[24:25], v[16:17], v[26:27] op_sel_hi:[1,0,1] neg_lo:[0,0,1] neg_hi:[0,0,1]
	v_pk_add_f32 v[34:35], v[34:35], v[68:69] op_sel_hi:[1,0]
	v_pk_mul_f32 v[68:69], v[188:189], v[126:127]
	v_pk_mul_f32 v[26:27], v[188:189], v[90:91]
	v_pk_fma_f32 v[72:73], v[82:83], v[16:17], v[68:69] op_sel_hi:[1,0,1] neg_lo:[0,0,1] neg_hi:[0,0,1]
	v_pk_mul_f32 v[68:69], v[188:189], v[124:125]
	v_pk_fma_f32 v[26:27], v[22:23], v[16:17], v[26:27] op_sel_hi:[1,0,1] neg_lo:[0,0,1] neg_hi:[0,0,1]
	v_pk_fma_f32 v[74:75], v[80:81], v[16:17], v[68:69] op_sel_hi:[1,0,1] neg_lo:[0,0,1] neg_hi:[0,0,1]
	v_pk_mul_f32 v[68:69], v[188:189], v[122:123]
	v_pk_mul_f32 v[22:23], v[188:189], v[88:89]
	v_pk_fma_f32 v[80:81], v[78:79], v[16:17], v[68:69] op_sel_hi:[1,0,1] neg_lo:[0,0,1] neg_hi:[0,0,1]
	v_pk_mul_f32 v[68:69], v[188:189], v[120:121]
	v_pk_mul_f32 v[14:15], v[188:189], v[14:15]
	v_pk_fma_f32 v[82:83], v[76:77], v[16:17], v[68:69] op_sel_hi:[1,0,1] neg_lo:[0,0,1] neg_hi:[0,0,1]
	v_pk_fma_f32 v[14:15], v[32:33], v[16:17], v[14:15] op_sel_hi:[1,0,1] neg_lo:[0,0,1] neg_hi:[0,0,1]
	v_pk_fma_f32 v[34:35], v[82:83], v[82:83], v[34:35]
	v_mul_f32_e32 v68, v83, v83
	v_pk_add_f32 v[34:35], v[34:35], v[68:69] op_sel_hi:[1,0]
	v_mul_f32_e32 v68, v81, v81
	v_pk_fma_f32 v[34:35], v[80:81], v[80:81], v[34:35]
; DI unsigned cvtpk(float lo, float hi) { f32x2_t v = {lo, hi}; bf16x2_t b = __builtin_convertvector(v, bf16x2_t); return __builtin_bit_cast(unsigned, b); }
; DI float swapsum(float m) { auto rr = __builtin_amdgcn_permlane32_swap(__float_as_uint(m), __float_as_uint(m), false, false); return __uint_as_float(rr[0]) + __uint_as_float(rr[1]); }
; template <int KIND> DI void attn_unit(const Params& P, int b, int h, int qb, char* shm, float lam, bool dry = false) {
;     ...
;             float ss = 0.f;
; #pragma unroll
;             for (int db = 0; db < NDB; ++db)
; #pragma unroll
;                 for (int r = 0; r < 16; ++r) { const float d = o[db][r] * rl - lam * comb[(db * 16 + r) * 64]; o[db][r] = d; ss += d * d; }
;             ss = swapsum(ss);
;             const float sc = __builtin_amdgcn_rsqf(ss * (1.0f / 128.0f) + RMS_EPS) * (1.0f - P.lam_init);
; #pragma unroll
;             for (int db = 0; db < NDB; ++db)
; #pragma unroll
;                 for (int g = 0; g < 4; g += 2) { u32x2 wp[2];
; #pragma unroll
;                     for (int e = 0; e < 2; ++e) { const f32x4 sg = *(const f32x4*)(P.subg + db * 32 + 8 * (g + e) + 4 * hi); const int r = 4 * (g + e);
;                         wp[e].x = cvtpk(o[db][r] * sc * sg[0], o[db][r + 1] * sc * sg[1]); wp[e].y = cvtpk(o[db][r + 2] * sc * sg[2], o[db][r + 3] * sc * sg[3]); }
	s_nop 0
	v_pk_add_f32 v[34:35], v[34:35], v[68:69] op_sel_hi:[1,0]
	v_mul_f32_e32 v68, v75, v75
	v_pk_fma_f32 v[34:35], v[74:75], v[74:75], v[34:35]
	s_nop 0
	v_pk_add_f32 v[34:35], v[34:35], v[68:69] op_sel_hi:[1,0]
	v_mul_f32_e32 v68, v73, v73
	v_pk_fma_f32 v[34:35], v[72:73], v[72:73], v[34:35]
	s_nop 0
	v_pk_add_f32 v[34:35], v[34:35], v[68:69] op_sel_hi:[1,0]
	v_pk_mul_f32 v[68:69], v[188:189], v[134:135]
	s_nop 0
	v_pk_fma_f32 v[68:69], v[58:59], v[16:17], v[68:69] op_sel_hi:[1,0,1] neg_lo:[0,0,1] neg_hi:[0,0,1]
	v_pk_mul_f32 v[58:59], v[188:189], v[132:133]
	s_nop 0
	v_pk_fma_f32 v[70:71], v[56:57], v[16:17], v[58:59] op_sel_hi:[1,0,1] neg_lo:[0,0,1] neg_hi:[0,0,1]
	v_pk_mul_f32 v[56:57], v[188:189], v[130:131]
	s_nop 0
	v_pk_fma_f32 v[76:77], v[54:55], v[16:17], v[56:57] op_sel_hi:[1,0,1] neg_lo:[0,0,1] neg_hi:[0,0,1]
	v_pk_mul_f32 v[54:55], v[188:189], v[128:129]
	s_nop 0
	v_pk_fma_f32 v[78:79], v[52:53], v[16:17], v[54:55] op_sel_hi:[1,0,1] neg_lo:[0,0,1] neg_hi:[0,0,1]
	s_nop 0
	v_pk_fma_f32 v[34:35], v[78:79], v[78:79], v[34:35]
	v_mul_f32_e32 v52, v79, v79
	v_pk_add_f32 v[34:35], v[34:35], v[52:53] op_sel_hi:[1,0]
	v_mul_f32_e32 v52, v77, v77
	v_pk_fma_f32 v[34:35], v[76:77], v[76:77], v[34:35]
	s_nop 0
	v_pk_add_f32 v[34:35], v[34:35], v[52:53] op_sel_hi:[1,0]
	v_mul_f32_e32 v52, v71, v71
	v_pk_fma_f32 v[34:35], v[70:71], v[70:71], v[34:35]
	s_nop 0
	v_pk_add_f32 v[34:35], v[34:35], v[52:53] op_sel_hi:[1,0]
	v_mul_f32_e32 v52, v69, v69
	v_pk_fma_f32 v[34:35], v[68:69], v[68:69], v[34:35]
	s_nop 0
	v_pk_add_f32 v[34:35], v[34:35], v[52:53] op_sel_hi:[1,0]
	v_pk_mul_f32 v[52:53], v[188:189], v[140:141]
	s_nop 0
	v_pk_fma_f32 v[54:55], v[66:67], v[16:17], v[52:53] op_sel_hi:[1,0,1] neg_lo:[0,0,1] neg_hi:[0,0,1]
	v_pk_mul_f32 v[52:53], v[188:189], v[138:139]
	s_nop 0
	v_pk_fma_f32 v[64:65], v[64:65], v[16:17], v[52:53] op_sel_hi:[1,0,1] neg_lo:[0,0,1] neg_hi:[0,0,1]
	v_pk_mul_f32 v[52:53], v[188:189], v[136:137]
	s_nop 0
	v_pk_fma_f32 v[62:63], v[62:63], v[16:17], v[52:53] op_sel_hi:[1,0,1] neg_lo:[0,0,1] neg_hi:[0,0,1]
	v_pk_mul_f32 v[52:53], v[188:189], v[118:119]
	s_nop 0
	v_pk_fma_f32 v[60:61], v[60:61], v[16:17], v[52:53] op_sel_hi:[1,0,1] neg_lo:[0,0,1] neg_hi:[0,0,1]
	s_nop 0
	v_pk_fma_f32 v[34:35], v[60:61], v[60:61], v[34:35]
	v_mul_f32_e32 v52, v61, v61
	v_pk_add_f32 v[34:35], v[34:35], v[52:53] op_sel_hi:[1,0]
	v_mul_f32_e32 v52, v63, v63
	v_pk_fma_f32 v[34:35], v[62:63], v[62:63], v[34:35]
	s_nop 0
	v_pk_add_f32 v[34:35], v[34:35], v[52:53] op_sel_hi:[1,0]
	v_mul_f32_e32 v52, v65, v65
	v_pk_fma_f32 v[34:35], v[64:65], v[64:65], v[34:35]
	s_nop 0
	v_pk_add_f32 v[34:35], v[34:35], v[52:53] op_sel_hi:[1,0]
	v_mul_f32_e32 v52, v55, v55
	v_pk_fma_f32 v[34:35], v[54:55], v[54:55], v[34:35]
	s_nop 0
	v_pk_add_f32 v[34:35], v[34:35], v[52:53] op_sel_hi:[1,0]
	v_pk_mul_f32 v[52:53], v[188:189], v[116:117]
	s_nop 0
	v_pk_fma_f32 v[42:43], v[42:43], v[16:17], v[52:53] op_sel_hi:[1,0,1] neg_lo:[0,0,1] neg_hi:[0,0,1]
	v_pk_mul_f32 v[52:53], v[188:189], v[114:115]
	s_nop 0
	v_pk_fma_f32 v[52:53], v[40:41], v[16:17], v[52:53] op_sel_hi:[1,0,1] neg_lo:[0,0,1] neg_hi:[0,0,1]
	v_pk_mul_f32 v[40:41], v[188:189], v[112:113]
	s_nop 0
	v_pk_fma_f32 v[56:57], v[38:39], v[16:17], v[40:41] op_sel_hi:[1,0,1] neg_lo:[0,0,1] neg_hi:[0,0,1]
	v_pk_mul_f32 v[38:39], v[188:189], v[110:111]
	v_pk_mul_f32 v[40:41], v[188:189], v[104:105]
	v_pk_fma_f32 v[58:59], v[36:37], v[16:17], v[38:39] op_sel_hi:[1,0,1] neg_lo:[0,0,1] neg_hi:[0,0,1]
	v_pk_fma_f32 v[40:41], v[46:47], v[16:17], v[40:41] op_sel_hi:[1,0,1] neg_lo:[0,0,1] neg_hi:[0,0,1]
	v_pk_fma_f32 v[34:35], v[58:59], v[58:59], v[34:35]
	v_mul_f32_e32 v36, v59, v59
	v_pk_add_f32 v[34:35], v[34:35], v[36:37] op_sel_hi:[1,0]
	v_mul_f32_e32 v36, v57, v57
	v_pk_fma_f32 v[34:35], v[56:57], v[56:57], v[34:35]
	v_pk_mul_f32 v[46:47], v[188:189], v[100:101]
	v_pk_add_f32 v[34:35], v[34:35], v[36:37] op_sel_hi:[1,0]
	v_mul_f32_e32 v36, v53, v53
	v_pk_fma_f32 v[34:35], v[52:53], v[52:53], v[34:35]
	v_pk_fma_f32 v[44:45], v[44:45], v[16:17], v[46:47] op_sel_hi:[1,0,1] neg_lo:[0,0,1] neg_hi:[0,0,1]
	v_pk_add_f32 v[34:35], v[34:35], v[36:37] op_sel_hi:[1,0]
	v_mul_f32_e32 v36, v43, v43
	v_pk_fma_f32 v[34:35], v[42:43], v[42:43], v[34:35]
	v_mul_f32_e32 v46, v45, v45
	v_pk_add_f32 v[36:37], v[34:35], v[36:37] op_sel_hi:[1,0]
	v_pk_mul_f32 v[38:39], v[188:189], v[106:107]
	v_pk_fma_f32 v[36:37], v[44:45], v[44:45], v[36:37]
	v_pk_fma_f32 v[38:39], v[48:49], v[16:17], v[38:39] op_sel_hi:[1,0,1] neg_lo:[0,0,1] neg_hi:[0,0,1]
	v_pk_add_f32 v[36:37], v[36:37], v[46:47] op_sel_hi:[1,0]
	v_mul_f32_e32 v46, v41, v41
	v_pk_fma_f32 v[36:37], v[40:41], v[40:41], v[36:37]
	v_pk_mul_f32 v[34:35], v[188:189], v[108:109]
	v_pk_add_f32 v[36:37], v[36:37], v[46:47] op_sel_hi:[1,0]
	v_mul_f32_e32 v46, v39, v39
	v_pk_fma_f32 v[36:37], v[38:39], v[38:39], v[36:37]
	v_pk_fma_f32 v[34:35], v[50:51], v[16:17], v[34:35] op_sel_hi:[1,0,1] neg_lo:[0,0,1] neg_hi:[0,0,1]
	v_pk_add_f32 v[36:37], v[36:37], v[46:47] op_sel_hi:[1,0]
	v_mul_f32_e32 v46, v35, v35
	v_pk_fma_f32 v[36:37], v[34:35], v[34:35], v[36:37]
	s_nop 0
	v_pk_add_f32 v[46:47], v[36:37], v[46:47] op_sel_hi:[1,0]
	v_pk_fma_f32 v[36:37], v[20:21], v[16:17], v[22:23] op_sel_hi:[1,0,1] neg_lo:[0,0,1] neg_hi:[0,0,1]
	s_nop 0
	v_pk_fma_f32 v[20:21], v[36:37], v[36:37], v[46:47]
	v_mul_f32_e32 v22, v37, v37
	v_pk_add_f32 v[20:21], v[20:21], v[22:23] op_sel_hi:[1,0]
	v_mul_f32_e32 v22, v27, v27
	v_pk_fma_f32 v[20:21], v[26:27], v[26:27], v[20:21]
	s_nop 0
	v_pk_add_f32 v[20:21], v[20:21], v[22:23] op_sel_hi:[1,0]
	v_mul_f32_e32 v22, v25, v25
	v_pk_fma_f32 v[20:21], v[24:25], v[24:25], v[20:21]
	s_nop 0
	v_pk_add_f32 v[20:21], v[20:21], v[22:23] op_sel_hi:[1,0]
	v_mul_f32_e32 v22, v19, v19
	v_pk_fma_f32 v[20:21], v[18:19], v[18:19], v[20:21]
	s_nop 0
	v_pk_add_f32 v[46:47], v[20:21], v[22:23] op_sel_hi:[1,0]
	v_pk_mul_f32 v[22:23], v[188:189], v[84:85]
	v_pk_mul_f32 v[20:21], v[188:189], v[86:87]
	v_pk_fma_f32 v[22:23], v[28:29], v[16:17], v[22:23] op_sel_hi:[1,0,1] neg_lo:[0,0,1] neg_hi:[0,0,1]
	v_pk_fma_f32 v[20:21], v[30:31], v[16:17], v[20:21] op_sel_hi:[1,0,1] neg_lo:[0,0,1] neg_hi:[0,0,1]
	v_pk_fma_f32 v[16:17], v[22:23], v[22:23], v[46:47]
	v_mul_f32_e32 v28, v23, v23
	v_pk_add_f32 v[16:17], v[16:17], v[28:29] op_sel_hi:[1,0]
	v_mul_f32_e32 v28, v21, v21
	v_pk_fma_f32 v[16:17], v[20:21], v[20:21], v[16:17]
	s_nop 0
	v_pk_add_f32 v[16:17], v[16:17], v[28:29] op_sel_hi:[1,0]
	v_mul_f32_e32 v28, v15, v15
	v_pk_fma_f32 v[16:17], v[14:15], v[14:15], v[16:17]
	s_nop 0
	v_pk_add_f32 v[16:17], v[16:17], v[28:29] op_sel_hi:[1,0]
	v_mul_f32_e32 v28, v13, v13
	v_pk_fma_f32 v[16:17], v[12:13], v[12:13], v[16:17]
	s_nop 0
	v_pk_add_f32 v[16:17], v[16:17], v[28:29] op_sel_hi:[1,0]
	s_nop 0
	v_mov_b32_e32 v17, v16
	s_nop 1
	v_permlane32_swap_b32_e32 v16, v17
	v_add_f32_e32 v16, v16, v17
	v_fmamk_f32 v16, v16, 0x3c000000, v237
	v_rsq_f32_e32 v16, v16
	s_nop 0
	v_mul_f32_e32 v16, v194, v16
	v_pk_mul_f32 v[28:29], v[102:103], v[16:17] op_sel_hi:[1,0]
	s_waitcnt vmcnt(0)
; DI unsigned cvtpk(float lo, float hi) { f32x2_t v = {lo, hi}; bf16x2_t b = __builtin_convertvector(v, bf16x2_t); return __builtin_bit_cast(unsigned, b); }
; #define ATT_WAIT_BAR() asm volatile("s_waitcnt vmcnt(0) lgkmcnt(0)\n\ts_barrier" ::: "memory")
; template <int KIND> DI void attn_unit(const Params& P, int b, int h, int qb, char* shm, float lam, bool dry = false) {
;     ...
;             const float sc = __builtin_amdgcn_rsqf(ss * (1.0f / 128.0f) + RMS_EPS) * (1.0f - P.lam_init);
; #pragma unroll
;             for (int db = 0; db < NDB; ++db)
; #pragma unroll
;                 for (int g = 0; g < 4; g += 2) { u32x2 wp[2];
; #pragma unroll
;                     for (int e = 0; e < 2; ++e) { const f32x4 sg = *(const f32x4*)(P.subg + db * 32 + 8 * (g + e) + 4 * hi); const int r = 4 * (g + e);
;                         wp[e].x = cvtpk(o[db][r] * sc * sg[0], o[db][r + 1] * sc * sg[1]); wp[e].y = cvtpk(o[db][r + 2] * sc * sg[2], o[db][r + 3] * sc * sg[3]); }
;                     store_pair16(orow + db * 32 + 8 * g, hi, wp[0], wp[1], dry); }
;         }
;         ATT_WAIT_BAR();
	v_writelane_b32 v255, 2, 61
	v_pk_mul_f32 v[8:9], v[148:149], v[28:29]
	v_pk_mul_f32 v[28:29], v[98:99], v[16:17] op_sel_hi:[1,0]
	v_cvt_pk_bf16_f32 v8, v8, v9
	v_pk_mul_f32 v[10:11], v[150:151], v[28:29]
	s_nop 0
	v_cvt_pk_bf16_f32 v9, v10, v11
	v_pk_mul_f32 v[10:11], v[96:97], v[16:17] op_sel_hi:[1,0]
	s_nop 0
	v_pk_mul_f32 v[4:5], v[152:153], v[10:11]
	s_nop 0
	v_cvt_pk_bf16_f32 v10, v4, v5
	v_pk_mul_f32 v[4:5], v[92:93], v[16:17] op_sel_hi:[1,0]
	s_nop 0
	v_permlane32_swap_b32_e32 v8, v10
	v_pk_mul_f32 v[4:5], v[154:155], v[4:5]
	s_nop 0
	v_cvt_pk_bf16_f32 v11, v4, v5
	s_nop 1
	v_permlane32_swap_b32_e32 v9, v11
	global_store_dwordx4 v[0:1], v[8:11], off
	s_nop 0
	s_nop 0
	v_pk_mul_f32 v[8:9], v[82:83], v[16:17] op_sel_hi:[1,0]
	v_pk_mul_f32 v[10:11], v[74:75], v[16:17] op_sel_hi:[1,0]
	s_nop 0
	v_pk_mul_f32 v[4:5], v[156:157], v[8:9]
	v_pk_mul_f32 v[8:9], v[80:81], v[16:17] op_sel_hi:[1,0]
	v_cvt_pk_bf16_f32 v4, v4, v5
	v_pk_mul_f32 v[6:7], v[158:159], v[8:9]
	s_nop 0
	v_cvt_pk_bf16_f32 v5, v6, v7
	s_nop 0
	v_pk_mul_f32 v[6:7], v[10:11], v[160:161]
	v_pk_mul_f32 v[10:11], v[72:73], v[16:17] op_sel_hi:[1,0]
	v_cvt_pk_bf16_f32 v6, v6, v7
	v_pk_mul_f32 v[8:9], v[10:11], v[162:163]
	s_nop 0
	v_permlane32_swap_b32_e32 v4, v6
	v_cvt_pk_bf16_f32 v7, v8, v9
	s_nop 1
	v_permlane32_swap_b32_e32 v5, v7
	global_store_dwordx4 v[0:1], v[4:7], off offset:32
	s_nop 0
	v_pk_mul_f32 v[8:9], v[78:79], v[16:17] op_sel_hi:[1,0]
	v_pk_mul_f32 v[10:11], v[70:71], v[16:17] op_sel_hi:[1,0]
	s_nop 0
	v_pk_mul_f32 v[4:5], v[8:9], v[164:165]
	v_pk_mul_f32 v[8:9], v[76:77], v[16:17] op_sel_hi:[1,0]
	v_cvt_pk_bf16_f32 v4, v4, v5
	v_pk_mul_f32 v[6:7], v[8:9], v[166:167]
	s_nop 0
	v_cvt_pk_bf16_f32 v5, v6, v7
	s_nop 0
	v_pk_mul_f32 v[6:7], v[10:11], v[168:169]
	v_pk_mul_f32 v[10:11], v[68:69], v[16:17] op_sel_hi:[1,0]
	v_cvt_pk_bf16_f32 v6, v6, v7
	v_pk_mul_f32 v[8:9], v[10:11], v[170:171]
	s_nop 0
	v_permlane32_swap_b32_e32 v4, v6
	v_cvt_pk_bf16_f32 v7, v8, v9
	s_nop 1
	v_permlane32_swap_b32_e32 v5, v7
	global_store_dwordx4 v[0:1], v[4:7], off offset:64
	s_nop 0
	v_pk_mul_f32 v[8:9], v[60:61], v[16:17] op_sel_hi:[1,0]
	v_pk_mul_f32 v[10:11], v[64:65], v[16:17] op_sel_hi:[1,0]
	s_nop 0
	v_pk_mul_f32 v[4:5], v[8:9], v[172:173]
	v_pk_mul_f32 v[8:9], v[62:63], v[16:17] op_sel_hi:[1,0]
	v_cvt_pk_bf16_f32 v4, v4, v5
	v_pk_mul_f32 v[6:7], v[8:9], v[174:175]
	s_nop 0
	v_cvt_pk_bf16_f32 v5, v6, v7
	s_nop 0
	v_pk_mul_f32 v[6:7], v[10:11], v[176:177]
	v_pk_mul_f32 v[10:11], v[54:55], v[16:17] op_sel_hi:[1,0]
	v_cvt_pk_bf16_f32 v6, v6, v7
	v_pk_mul_f32 v[8:9], v[10:11], v[178:179]
	s_nop 0
	v_permlane32_swap_b32_e32 v4, v6
	v_cvt_pk_bf16_f32 v7, v8, v9
	s_nop 1
	v_permlane32_swap_b32_e32 v5, v7
	global_store_dwordx4 v[0:1], v[4:7], off offset:96
	s_nop 0
	v_pk_mul_f32 v[8:9], v[58:59], v[16:17] op_sel_hi:[1,0]
	v_pk_mul_f32 v[10:11], v[52:53], v[16:17] op_sel_hi:[1,0]
	s_nop 0
	v_pk_mul_f32 v[4:5], v[8:9], v[180:181]
	v_pk_mul_f32 v[8:9], v[56:57], v[16:17] op_sel_hi:[1,0]
	v_cvt_pk_bf16_f32 v4, v4, v5
	v_pk_mul_f32 v[6:7], v[8:9], v[182:183]
	s_nop 0
	v_cvt_pk_bf16_f32 v5, v6, v7
	s_nop 0
	v_pk_mul_f32 v[6:7], v[10:11], v[184:185]
	v_pk_mul_f32 v[10:11], v[42:43], v[16:17] op_sel_hi:[1,0]
	v_cvt_pk_bf16_f32 v6, v6, v7
	v_pk_mul_f32 v[8:9], v[10:11], v[186:187]
	s_nop 0
	v_permlane32_swap_b32_e32 v4, v6
	v_cvt_pk_bf16_f32 v7, v8, v9
	s_nop 1
	v_permlane32_swap_b32_e32 v5, v7
	global_store_dwordx4 v[0:1], v[4:7], off offset:128
	s_nop 0
	v_pk_mul_f32 v[8:9], v[44:45], v[16:17] op_sel_hi:[1,0]
	v_pk_mul_f32 v[10:11], v[38:39], v[16:17] op_sel_hi:[1,0]
	s_nop 0
	v_pk_mul_f32 v[4:5], v[8:9], v[208:209]
	v_pk_mul_f32 v[8:9], v[40:41], v[16:17] op_sel_hi:[1,0]
	v_cvt_pk_bf16_f32 v4, v4, v5
	v_pk_mul_f32 v[6:7], v[8:9], v[210:211]
	s_nop 0
	v_cvt_pk_bf16_f32 v5, v6, v7
	s_nop 0
	v_pk_mul_f32 v[6:7], v[10:11], v[220:221]
	v_pk_mul_f32 v[10:11], v[34:35], v[16:17] op_sel_hi:[1,0]
	v_cvt_pk_bf16_f32 v6, v6, v7
	v_pk_mul_f32 v[8:9], v[10:11], v[222:223]
	s_nop 0
	v_permlane32_swap_b32_e32 v4, v6
	v_cvt_pk_bf16_f32 v7, v8, v9
	s_nop 1
	v_permlane32_swap_b32_e32 v5, v7
	global_store_dwordx4 v[0:1], v[4:7], off offset:160
	s_nop 0
	v_pk_mul_f32 v[8:9], v[36:37], v[16:17] op_sel_hi:[1,0]
	v_pk_mul_f32 v[10:11], v[24:25], v[16:17] op_sel_hi:[1,0]
	s_nop 0
	v_pk_mul_f32 v[4:5], v[8:9], v[224:225]
	v_pk_mul_f32 v[8:9], v[26:27], v[16:17] op_sel_hi:[1,0]
	v_cvt_pk_bf16_f32 v4, v4, v5
	v_pk_mul_f32 v[6:7], v[8:9], v[226:227]
	s_nop 0
	v_cvt_pk_bf16_f32 v5, v6, v7
	s_nop 0
	v_pk_mul_f32 v[6:7], v[10:11], v[228:229]
	v_pk_mul_f32 v[10:11], v[18:19], v[16:17] op_sel_hi:[1,0]
	v_cvt_pk_bf16_f32 v6, v6, v7
	v_pk_mul_f32 v[8:9], v[10:11], v[230:231]
	s_nop 0
	v_permlane32_swap_b32_e32 v4, v6
	v_cvt_pk_bf16_f32 v7, v8, v9
	s_nop 1
	v_permlane32_swap_b32_e32 v5, v7
	global_store_dwordx4 v[0:1], v[4:7], off offset:192
	s_nop 0
	v_pk_mul_f32 v[8:9], v[22:23], v[16:17] op_sel_hi:[1,0]
	v_pk_mul_f32 v[10:11], v[14:15], v[16:17] op_sel_hi:[1,0]
	s_nop 0
	v_pk_mul_f32 v[4:5], v[8:9], v[232:233]
	v_pk_mul_f32 v[8:9], v[20:21], v[16:17] op_sel_hi:[1,0]
	v_cvt_pk_bf16_f32 v4, v4, v5
	v_pk_mul_f32 v[6:7], v[8:9], v[234:235]
	s_nop 0
	v_cvt_pk_bf16_f32 v5, v6, v7
	s_nop 0
	v_pk_mul_f32 v[6:7], v[10:11], v[190:191]
	v_pk_mul_f32 v[10:11], v[12:13], v[16:17] op_sel_hi:[1,0]
	v_cvt_pk_bf16_f32 v6, v6, v7
	v_pk_mul_f32 v[8:9], v[10:11], v[192:193]
	s_nop 0
	v_permlane32_swap_b32_e32 v4, v6
	v_cvt_pk_bf16_f32 v7, v8, v9
	s_nop 1
	v_permlane32_swap_b32_e32 v5, v7
	global_store_dwordx4 v[0:1], v[4:7], off offset:224
	s_branch .LBB0_317

; template <int KIND> DI void attn_unit(const Params& P, int b, int h, int qb, char* shm, float lam, bool dry = false) {
;     ...
;     const float rl = __builtin_amdgcn_rcpf(swapsum(lsum));
;     bf16_t* orow = P.Qp + (rowbase + qrow0 + r32) * PITCH + ((KIND == 0) ? h * 128 : qoff);
;     ATT_WAIT_BAR();
;     if (KIND == 0) {
;         LAS float* comb = (LAS float*)shm3 + (size_t)(wid & 3) * 4096 + lane;
;         if (m == 1) {
; #pragma unroll
;             for (int db = 0; db < NDB; ++db)
; #pragma unroll
;                 for (int r = 0; r < 16; ++r) comb[(db * 16 + r) * 64] = o[db][r] * rl;
;         }
;         ATT_WAIT_BAR();
;         if (m == 0) {
;             float ss = 0.f;
; #pragma unroll
;             for (int db = 0; db < NDB; ++db)
; #pragma unroll
;                 for (int r = 0; r < 16; ++r) { const float d = o[db][r] * rl - lam * comb[(db * 16 + r) * 64]; o[db][r] = d; ss += d * d; }
;             ss = swapsum(ss);
;             const float sc = __builtin_amdgcn_rsqf(ss * (1.0f / 128.0f) + RMS_EPS) * (1.0f - P.lam_init);
; #pragma unroll
;             for (int db = 0; db < NDB; ++db)
; #pragma unroll
;                 for (int g = 0; g < 4; g += 2) { u32x2 wp[2];
; #pragma unroll
;                     for (int e = 0; e < 2; ++e) { const f32x4 sg = *(const f32x4*)(P.subg + db * 32 + 8 * (g + e) + 4 * hi); const int r = 4 * (g + e);
;                         wp[e].x = cvtpk(o[db][r] * sc * sg[0], o[db][r + 1] * sc * sg[1]); wp[e].y = cvtpk(o[db][r + 2] * sc * sg[2], o[db][r + 3] * sc * sg[3]); }
;                     store_pair16(orow + db * 32 + 8 * g, hi, wp[0], wp[1], dry); }
;         }
;         ATT_WAIT_BAR();
;     } else {
; #pragma unroll
;         for (int db = 0; db < NDB; ++db)
; #pragma unroll
;             for (int g = 0; g < 4; g += 2) { u32x2 wp[2];
; #pragma unroll
;                 for (int e = 0; e < 2; ++e) { const int r = 4 * (g + e); wp[e].x = cvtpk(o[db][r] * rl, o[db][r + 1] * rl); wp[e].y = cvtpk(o[db][r + 2] * rl, o[db][r + 3] * rl); }
;                 store_pair16(orow + db * 32 + 8 * g, hi, wp[0], wp[1], dry); }
; DI void attn_phase(const Params& P, char* shm) {
;     ...
;         const unsigned q = (xcd + k) & 7u; unsigned* cnt = P.counter + 16 * q;
;         for (;;) {
;             if (tid == 0) su[0] = atomicAdd(cnt, 1u);
;             ATT_WAIT_BAR();
;             const unsigned ui = su[0];
;             ATT_WAIT_BAR();
.LBB0_437:
	v_mov_b32_e32 v0, v159
	s_nop 1
	v_permlane32_swap_b32_e32 v159, v0
	v_add_f32_e32 v0, v159, v0
	v_rcp_f32_e32 v0, v0
	s_waitcnt vmcnt(0) lgkmcnt(0)
	s_barrier
	v_readlane_b32 s100, v255, 47
	v_readlane_b32 s101, v255, 48
	v_readlane_b32 vcc_lo, v255, 39
	v_readlane_b32 vcc_hi, v255, 40
	v_mov_b32_e32 v218, 1
	v_mov_b32_e32 v219, 0
	s_mov_b64 exec, vcc
	s_nop 1
	global_atomic_add v218, v219, v218, s[100:101] sc0
	s_mov_b64 exec, -1
	v_writelane_b32 v255, 3, 61
	s_nop 0
	s_nop 0
	v_pk_mul_f32 v[4:5], v[4:5], v[0:1] op_sel_hi:[1,0]
	v_pk_mul_f32 v[6:7], v[6:7], v[0:1] op_sel_hi:[1,0]
	v_cvt_pk_bf16_f32 v4, v4, v5
	v_cvt_pk_bf16_f32 v5, v6, v7
	v_pk_mul_f32 v[6:7], v[8:9], v[0:1] op_sel_hi:[1,0]
	v_pk_mul_f32 v[8:9], v[10:11], v[0:1] op_sel_hi:[1,0]
	v_cvt_pk_bf16_f32 v6, v6, v7
	v_cvt_pk_bf16_f32 v7, v8, v9
	s_nop 0
	v_permlane32_swap_b32_e32 v4, v6
	v_permlane32_swap_b32_e32 v5, v7
	global_store_dwordx4 v[152:153], v[4:7], off offset:1024
	v_pk_mul_f32 v[8:9], v[18:19], v[0:1] op_sel_hi:[1,0]
	s_nop 0
	v_pk_mul_f32 v[4:5], v[12:13], v[0:1] op_sel_hi:[1,0]
	v_pk_mul_f32 v[6:7], v[14:15], v[0:1] op_sel_hi:[1,0]
	v_cvt_pk_bf16_f32 v4, v4, v5
	v_cvt_pk_bf16_f32 v5, v6, v7
	v_pk_mul_f32 v[6:7], v[16:17], v[0:1] op_sel_hi:[1,0]
	s_nop 0
	v_cvt_pk_bf16_f32 v6, v6, v7
	v_cvt_pk_bf16_f32 v7, v8, v9
	s_nop 0
	v_permlane32_swap_b32_e32 v4, v6
	v_permlane32_swap_b32_e32 v5, v7
	global_store_dwordx4 v[152:153], v[4:7], off offset:1056
	v_pk_mul_f32 v[8:9], v[26:27], v[0:1] op_sel_hi:[1,0]
	s_nop 0
	v_pk_mul_f32 v[4:5], v[20:21], v[0:1] op_sel_hi:[1,0]
	v_pk_mul_f32 v[6:7], v[22:23], v[0:1] op_sel_hi:[1,0]
	v_cvt_pk_bf16_f32 v4, v4, v5
	v_cvt_pk_bf16_f32 v5, v6, v7
	v_pk_mul_f32 v[6:7], v[24:25], v[0:1] op_sel_hi:[1,0]
	s_nop 0
	v_cvt_pk_bf16_f32 v6, v6, v7
	v_cvt_pk_bf16_f32 v7, v8, v9
	s_nop 0
	v_permlane32_swap_b32_e32 v4, v6
	v_permlane32_swap_b32_e32 v5, v7
	global_store_dwordx4 v[152:153], v[4:7], off offset:1088
	s_nop 1
	v_pk_mul_f32 v[4:5], v[28:29], v[0:1] op_sel_hi:[1,0]
	v_pk_mul_f32 v[6:7], v[30:31], v[0:1] op_sel_hi:[1,0]
	v_cvt_pk_bf16_f32 v4, v4, v5
	v_cvt_pk_bf16_f32 v5, v6, v7
	v_pk_mul_f32 v[6:7], v[32:33], v[0:1] op_sel_hi:[1,0]
	v_pk_mul_f32 v[0:1], v[34:35], v[0:1] op_sel_hi:[1,0]
	v_cvt_pk_bf16_f32 v6, v6, v7
	v_cvt_pk_bf16_f32 v7, v0, v1
	s_nop 0
	v_permlane32_swap_b32_e32 v4, v6
	v_permlane32_swap_b32_e32 v5, v7
	global_store_dwordx4 v[152:153], v[4:7], off offset:1120
	s_cbranch_execnz .LBB0_318
	s_branch .LBB0_378
